# grid barriers: XCD-hierarchical (per-XCC arrival counter, one L2 writeback per XCD by its last arriver, top counter, per-XCC release) instead of one flat counter with a writeback per workgroup
# speedup vs baseline: 1.0482x; 1.0482x over previous
; #define GSYNC() do { ++bar_n; grid_barrier(bar_ctr, bar_n * (unsigned)G); } while (0)
; __device__ __forceinline__ void grid_barrier(unsigned* ctr, unsigned target) {
;     asm volatile("s_waitcnt vmcnt(0)" ::: "memory");
;     __syncthreads();
;     if (threadIdx.x == 0) {
;         __builtin_amdgcn_fence(__ATOMIC_RELEASE, "agent");
;         asm volatile("s_waitcnt vmcnt(0)" ::: "memory");
;         __hip_atomic_fetch_add(ctr, 1u, __ATOMIC_RELAXED, __HIP_MEMORY_SCOPE_AGENT);
;         unsigned spins = 0;
;         while (__hip_atomic_load(ctr, __ATOMIC_RELAXED, __HIP_MEMORY_SCOPE_AGENT) < target) { __builtin_amdgcn_s_sleep(2); if (++spins > (1u << 24)) break; }
;         __builtin_amdgcn_fence(__ATOMIC_ACQUIRE, "agent");
;         asm volatile("s_waitcnt vmcnt(0)" ::: "memory");
;     }
;     __syncthreads();
; }
; __global__ void __launch_bounds__(512, 2) mk_fwd(Args a) {
;     ...
;     GSYNC();
.LBB0_65:
	s_waitcnt vmcnt(0)
	s_waitcnt lgkmcnt(0)
	s_barrier
	s_mov_b64 s[4:5], exec
	v_readlane_b32 s0, v255, 0
	v_readlane_b32 s1, v255, 1
	s_and_b64 s[0:1], s[4:5], s[0:1]
	s_mov_b64 exec, s[0:1]
	s_cbranch_execz .LBB0_82
	s_getreg_b32 s6, hwreg(HW_REG_XCC_ID, 0, 4)
	s_and_b32 s6, s6, 7
	s_lshl_b32 s6, s6, 8
	s_add_i32 s7, s6, 0x16000
	v_mov_b32_e32 v0, s7
	v_mov_b32_e32 v1, 1
	global_atomic_add v1, v0, v1, s[22:23] sc0
	s_waitcnt vmcnt(0)
	v_readfirstlane_b32 s7, v1
	s_nop 1
	s_add_i32 s7, s7, 1
	s_cmp_lg_u32 s7, 32
	s_cbranch_scc1 .Lmy_gb1_follow
	buffer_wbl2 sc1
	s_waitcnt vmcnt(0)
	v_mov_b32_e32 v0, 0x18000
	v_mov_b32_e32 v1, 1
	global_atomic_add v1, v0, v1, s[22:23] sc0
	s_waitcnt vmcnt(0)
	v_readfirstlane_b32 s7, v1
	s_nop 1
	s_add_i32 s7, s7, 1
	v_mov_b32_e32 v0, 0x18100
	s_cmp_lg_u32 s7, 8
	s_cbranch_scc1 .Lmy_gb1_topwait
	v_mov_b32_e32 v1, 1
	global_atomic_add v0, v1, s[22:23]
	s_branch .Lmy_gb1_rel
.Lmy_gb1_topwait:
	s_mov_b32 s8, 0x400000
.Lmy_gb1_topspin:
	global_load_dword v1, v0, s[22:23] sc1
	s_waitcnt vmcnt(0)
	v_readfirstlane_b32 s7, v1
	s_nop 1
	s_cmp_ge_u32 s7, 1
	s_cbranch_scc1 .Lmy_gb1_rel
	s_sleep 1
	s_add_i32 s8, s8, -1
	s_cmp_lg_u32 s8, 0
	s_cbranch_scc1 .Lmy_gb1_topspin
.Lmy_gb1_rel:
	buffer_inv sc1
	s_add_i32 s7, s6, 0x17000
	v_mov_b32_e32 v0, s7
	v_mov_b32_e32 v1, 1
	global_atomic_add v0, v1, s[22:23]
	s_waitcnt vmcnt(0)
	s_branch .Lmy_gb1_done
.Lmy_gb1_follow:
	s_add_i32 s7, s6, 0x17000
	v_mov_b32_e32 v0, s7
	s_mov_b32 s8, 0x400000

; #define LAS __attribute__((address_space(3)))
; __global__ void __launch_bounds__(512, 2) mk_fwd(Args a) {
;     ...
;     { LAS int* vslot = (LAS int*)(lds + RING_BYTES);
;       if (threadIdx.x == 0) { const unsigned my_rank = *(LAS unsigned*)(lds + RING_BYTES + 64); bool ok = (G % 8 == 0) && (my_xcc < 8u);
;           for (int j = 0; j < 8; ++j) ok = ok && (__hip_atomic_load(bar_ctr + 512 + 64 * j, __ATOMIC_RELAXED, __HIP_MEMORY_SCOPE_AGENT) == (unsigned)(G / 8));
;           *vslot = ok ? (int)(my_rank * 8u + my_xcc) : bx; }
;       __syncthreads(); vbx = __builtin_amdgcn_readfirstlane(*vslot); }
.Lmy_gb1_done:
.LBB0_82:
	s_or_b64 exec, exec, s[4:5]
	s_barrier
	s_mov_b64 s[4:5], exec
	v_readlane_b32 s0, v255, 0
	v_readlane_b32 s1, v255, 1
	s_and_b64 s[0:1], s[4:5], s[0:1]
	s_mov_b64 exec, s[0:1]
	s_cbranch_execz .LBB0_93
	s_add_i32 s1, 0, 0x20040
	s_and_b32 s0, s3, 15
	v_mov_b32_e32 v0, s1
	s_and_b32 s1, s24, 7
	ds_read_b32 v0, v0
	s_cmp_eq_u32 s1, 0
	s_cselect_b64 s[6:7], -1, 0
	s_cmp_lt_u32 s0, 8
	s_cselect_b64 s[8:9], -1, 0
	s_and_b64 s[6:7], s[6:7], s[8:9]
	s_andn2_b64 vcc, exec, s[6:7]
	s_mov_b64 s[6:7], 0
	s_cbranch_vccnz .LBB0_92
	v_mov_b32_e32 v1, 0
	global_load_dword v2, v1, s[22:23] offset:2048 sc1
	s_ashr_i32 s1, s24, 31
	s_lshr_b32 s1, s1, 29
	s_add_i32 s1, s24, s1
	s_ashr_i32 s1, s1, 3
	s_waitcnt vmcnt(0)
	v_cmp_ne_u32_e32 vcc, s1, v2
	s_cbranch_vccnz .LBB0_92
	global_load_dword v1, v1, s[22:23] offset:2304 sc1
	s_waitcnt vmcnt(0)
	v_cmp_ne_u32_e32 vcc, s1, v1
	s_cbranch_vccnz .LBB0_92
	v_mov_b32_e32 v1, 0
	global_load_dword v2, v1, s[22:23] offset:2560 sc1
	s_waitcnt vmcnt(0)
	v_cmp_ne_u32_e32 vcc, s1, v2
	s_cbranch_vccnz .LBB0_92
	global_load_dword v1, v1, s[22:23] offset:2816 sc1
	s_waitcnt vmcnt(0)
	v_cmp_ne_u32_e32 vcc, s1, v1
	s_cbranch_vccnz .LBB0_92
	v_mov_b32_e32 v1, 0
	global_load_dword v2, v1, s[22:23] offset:3072 sc1
	s_waitcnt vmcnt(0)
	v_cmp_ne_u32_e32 vcc, s1, v2
	s_cbranch_vccnz .LBB0_92
	global_load_dword v1, v1, s[22:23] offset:3328 sc1
	s_waitcnt vmcnt(0)
	v_cmp_ne_u32_e32 vcc, s1, v1
	s_cbranch_vccnz .LBB0_92
	v_mov_b32_e32 v1, 0
	global_load_dword v2, v1, s[22:23] offset:3584 sc1
	s_waitcnt vmcnt(0)
	v_cmp_ne_u32_e32 vcc, s1, v2
	s_cbranch_vccnz .LBB0_92
	global_load_dword v1, v1, s[22:23] offset:3840 sc1
	s_waitcnt vmcnt(0)
	v_cmp_eq_u32_e64 s[6:7], s1, v1

; #define GSYNC() do { ++bar_n; grid_barrier(bar_ctr, bar_n * (unsigned)G); } while (0)
; __device__ __forceinline__ void grid_barrier(unsigned* ctr, unsigned target) {
;     asm volatile("s_waitcnt vmcnt(0)" ::: "memory");
;     __syncthreads();
;     if (threadIdx.x == 0) {
;         __builtin_amdgcn_fence(__ATOMIC_RELEASE, "agent");
;         asm volatile("s_waitcnt vmcnt(0)" ::: "memory");
;         __hip_atomic_fetch_add(ctr, 1u, __ATOMIC_RELAXED, __HIP_MEMORY_SCOPE_AGENT);
;         unsigned spins = 0;
;         while (__hip_atomic_load(ctr, __ATOMIC_RELAXED, __HIP_MEMORY_SCOPE_AGENT) < target) { __builtin_amdgcn_s_sleep(2); if (++spins > (1u << 24)) break; }
;         __builtin_amdgcn_fence(__ATOMIC_ACQUIRE, "agent");
;         asm volatile("s_waitcnt vmcnt(0)" ::: "memory");
;     }
;     __syncthreads();
; }
; __global__ void __launch_bounds__(512, 2) mk_fwd(Args a) {
;     ...
;     GSYNC();
.LBB0_117:
	s_waitcnt vmcnt(0)
	v_readlane_b32 s4, v255, 0
	v_readlane_b32 s5, v255, 1
	s_waitcnt vmcnt(0) lgkmcnt(0)
	s_barrier
	s_and_saveexec_b64 s[0:1], s[4:5]
	s_xor_b64 s[4:5], exec, s[0:1]
	s_cbranch_execz .LBB0_134
	s_getreg_b32 s6, hwreg(HW_REG_XCC_ID, 0, 4)
	s_and_b32 s6, s6, 7
	s_lshl_b32 s6, s6, 8
	s_add_i32 s7, s6, 0x16000
	v_mov_b32_e32 v0, s7
	v_mov_b32_e32 v1, 1
	global_atomic_add v1, v0, v1, s[22:23] sc0
	s_waitcnt vmcnt(0)
	v_readfirstlane_b32 s7, v1
	s_nop 1
	s_add_i32 s7, s7, 1
	s_cmp_lg_u32 s7, 64
	s_cbranch_scc1 .Lmy_gb2_follow
	buffer_wbl2 sc1
	s_waitcnt vmcnt(0)
	v_mov_b32_e32 v0, 0x18000
	v_mov_b32_e32 v1, 1
	global_atomic_add v1, v0, v1, s[22:23] sc0
	s_waitcnt vmcnt(0)
	v_readfirstlane_b32 s7, v1
	s_nop 1
	s_add_i32 s7, s7, 1
	v_mov_b32_e32 v0, 0x18100
	s_cmp_lg_u32 s7, 16
	s_cbranch_scc1 .Lmy_gb2_topwait
	v_mov_b32_e32 v1, 1
	global_atomic_add v0, v1, s[22:23]
	s_branch .Lmy_gb2_rel

; __device__ __forceinline__ void grid_barrier(unsigned* ctr, unsigned target) {
;     ...
;         while (__hip_atomic_load(ctr, __ATOMIC_RELAXED, __HIP_MEMORY_SCOPE_AGENT) < target) { __builtin_amdgcn_s_sleep(2); if (++spins > (1u << 24)) break; }
;         __builtin_amdgcn_fence(__ATOMIC_ACQUIRE, "agent");
.Lmy_gb2_topspin:
	global_load_dword v1, v0, s[22:23] sc1
	s_waitcnt vmcnt(0)
	v_readfirstlane_b32 s7, v1
	s_nop 1
	s_cmp_ge_u32 s7, 2
	s_cbranch_scc1 .Lmy_gb2_rel
	s_sleep 1
	s_add_i32 s8, s8, -1
	s_cmp_lg_u32 s8, 0
	s_cbranch_scc1 .Lmy_gb2_topspin

; #define LAS __attribute__((address_space(3)))
;     int tid_l = threadIdx.x; asm volatile("" : "+v"(tid_l));
;     const int tid = tid_l, lane = tid & 63, wave = __builtin_amdgcn_readfirstlane(tid >> 6), qi = lane & 15, g = lane >> 4;
;     LAS unsigned char* ldsK = lds + L_K; LAS unsigned char* ldsV = lds + L_V; LAS float* tbl = (LAS float*)(lds + L_T); LAS float* pmt = (LAS float*)(lds + L_PM);
;     const int G = gridDim.x, bx = blockIdx.x;
;     const int na0 = (int)((long)bx * NITEM_A / G), nA = (int)((long)(bx + 1) * NITEM_A / G) - na0;
;     const int nb0 = (int)((long)bx * NITEM_B / G), nB = (int)((long)(bx + 1) * NITEM_B / G) - nb0;
.Lmy_gb2_done:
.LBB0_134:
	s_or_b64 exec, exec, s[4:5]
	v_and_b32_e32 v242, 7, v254
	v_lshlrev_b32_e32 v242, 2, v242
	global_load_dword v241, v242, s[10:11]
	s_waitcnt vmcnt(0)
	s_mul_hi_i32 s5, s2, 0x500
	s_mul_i32 s4, s2, 0x500
	s_or_b64 s[0:1], s[4:5], s[24:25]
	v_mov_b32_e32 v147, v254
	s_mov_b32 s0, 0
	s_barrier
	s_cmp_lg_u64 s[0:1], 0
	v_readfirstlane_b32 s48, v147
	s_cbranch_scc0 .LBB0_149
	s_ashr_i32 s8, s25, 31
	s_add_u32 s0, s24, s8
	s_mov_b32 s9, s8
	s_addc_u32 s1, s25, s8
	s_xor_b64 s[12:13], s[0:1], s[8:9]
	v_cvt_f32_u32_e32 v0, s12
	v_cvt_f32_u32_e32 v1, s13
	s_sub_u32 s3, 0, s12
	s_subb_u32 s14, 0, s13
	v_fmamk_f32 v0, v1, 0x4f800000, v0
	v_rcp_f32_e32 v0, v0
	s_nop 0
	v_mul_f32_e32 v0, 0x5f7ffffc, v0
	v_mul_f32_e32 v1, 0x2f800000, v0
	v_trunc_f32_e32 v1, v1
	v_fmamk_f32 v0, v1, 0xcf800000, v0
	v_cvt_u32_f32_e32 v1, v1
	v_cvt_u32_f32_e32 v0, v0
	v_readfirstlane_b32 s15, v1
	v_readfirstlane_b32 s0, v0
	s_mul_i32 s1, s3, s15
	s_mul_hi_u32 s45, s3, s0
	s_mul_i32 s44, s14, s0
	s_add_i32 s1, s45, s1
	s_add_i32 s1, s1, s44
	s_mul_i32 s46, s3, s0
	s_mul_i32 s45, s0, s1
	s_mul_hi_u32 s47, s0, s46
	s_mul_hi_u32 s44, s0, s1
	s_add_u32 s45, s47, s45
	s_addc_u32 s44, 0, s44
	s_mul_hi_u32 s49, s15, s46
	s_mul_i32 s46, s15, s46
	s_add_u32 s45, s45, s46
	s_mul_hi_u32 s47, s15, s1
	s_addc_u32 s44, s44, s49
	s_addc_u32 s45, s47, 0
	s_mul_i32 s1, s15, s1
	s_add_u32 s1, s44, s1
	s_addc_u32 s44, 0, s45
	s_add_u32 s45, s0, s1
	s_cselect_b64 s[0:1], -1, 0
	s_cmp_lg_u64 s[0:1], 0
	s_addc_u32 s15, s15, s44
	s_mul_i32 s0, s3, s15
	s_mul_hi_u32 s1, s3, s45
	s_add_i32 s0, s1, s0
	s_mul_i32 s14, s14, s45
	s_add_i32 s0, s0, s14
	s_mul_i32 s3, s3, s45
	s_mul_hi_u32 s14, s15, s3
	s_mul_i32 s44, s15, s3
	s_mul_i32 s47, s45, s0
	s_mul_hi_u32 s3, s45, s3
	s_mul_hi_u32 s46, s45, s0
	s_add_u32 s3, s3, s47
	s_addc_u32 s46, 0, s46
	s_add_u32 s3, s3, s44
	s_mul_hi_u32 s1, s15, s0
	s_addc_u32 s3, s46, s14
	s_addc_u32 s1, s1, 0
	s_mul_i32 s0, s15, s0
	s_add_u32 s0, s3, s0
	s_addc_u32 s3, 0, s1
	s_add_u32 s44, s45, s0
	s_cselect_b64 s[0:1], -1, 0
	s_cmp_lg_u64 s[0:1], 0
	s_addc_u32 s3, s15, s3
	s_ashr_i32 s0, s5, 31
	s_add_u32 s14, s4, s0
	s_mov_b32 s1, s0
	s_addc_u32 s15, s5, s0
	s_xor_b64 s[14:15], s[14:15], s[0:1]
	s_mul_i32 s45, s14, s3
	s_mul_hi_u32 s46, s14, s44
	s_mul_hi_u32 s5, s14, s3
	s_add_u32 s45, s46, s45
	s_addc_u32 s5, 0, s5
	s_mul_hi_u32 s47, s15, s44
	s_mul_i32 s44, s15, s44
	s_add_u32 s44, s45, s44
	s_mul_hi_u32 s46, s15, s3
	s_addc_u32 s5, s5, s47
	s_addc_u32 s44, s46, 0
	s_mul_i32 s3, s15, s3
	s_add_u32 s3, s5, s3
	s_addc_u32 s5, 0, s44
	s_mul_i32 s44, s12, s5
	s_mul_hi_u32 s45, s12, s3
	s_add_i32 s44, s45, s44
	s_mul_i32 s45, s13, s3
	s_add_i32 s49, s44, s45
	s_sub_i32 s46, s15, s49
	s_mul_i32 s44, s12, s3
	s_sub_u32 s14, s14, s44
	s_cselect_b64 s[44:45], -1, 0
	s_cmp_lg_u64 s[44:45], 0
	s_subb_u32 s50, s46, s13
	s_sub_u32 s51, s14, s12
	s_cselect_b64 s[46:47], -1, 0
	s_cmp_lg_u64 s[46:47], 0
	s_subb_u32 s46, s50, 0
	s_cmp_ge_u32 s46, s13
	s_cselect_b32 s47, -1, 0
	s_cmp_ge_u32 s51, s12
	s_cselect_b32 s50, -1, 0
	s_cmp_eq_u32 s46, s13
	s_cselect_b32 s46, s50, s47
	s_add_u32 s47, s3, 1
	s_addc_u32 s50, s5, 0
	s_add_u32 s51, s3, 2
	s_addc_u32 s54, s5, 0
	s_cmp_lg_u32 s46, 0
	s_cselect_b32 s46, s51, s47
	s_cselect_b32 s47, s54, s50
	s_cmp_lg_u64 s[44:45], 0
	s_subb_u32 s15, s15, s49
	s_cmp_ge_u32 s15, s13
	s_cselect_b32 s44, -1, 0
	s_cmp_ge_u32 s14, s12
	s_cselect_b32 s12, -1, 0
	s_cmp_eq_u32 s15, s13
	s_cselect_b32 s12, s12, s44
	s_cmp_lg_u32 s12, 0
	s_cselect_b32 s13, s47, s5
	s_cselect_b32 s12, s46, s3
	s_xor_b64 s[0:1], s[0:1], s[8:9]
	s_xor_b64 s[8:9], s[12:13], s[0:1]
	s_sub_u32 s12, s8, s0
	v_cvt_f32_u32_e32 v0, s24
	s_cbranch_execnz .LBB0_137

; #define GSYNC() do { ++bar_n; grid_barrier(bar_ctr, bar_n * (unsigned)G); } while (0)
; __device__ __forceinline__ void grid_barrier(unsigned* ctr, unsigned target) {
;     asm volatile("s_waitcnt vmcnt(0)" ::: "memory");
;     __syncthreads();
;     if (threadIdx.x == 0) {
;         __builtin_amdgcn_fence(__ATOMIC_RELEASE, "agent");
;         asm volatile("s_waitcnt vmcnt(0)" ::: "memory");
;         __hip_atomic_fetch_add(ctr, 1u, __ATOMIC_RELAXED, __HIP_MEMORY_SCOPE_AGENT);
;         unsigned spins = 0;
;         while (__hip_atomic_load(ctr, __ATOMIC_RELAXED, __HIP_MEMORY_SCOPE_AGENT) < target) { __builtin_amdgcn_s_sleep(2); if (++spins > (1u << 24)) break; }
;         __builtin_amdgcn_fence(__ATOMIC_ACQUIRE, "agent");
;         asm volatile("s_waitcnt vmcnt(0)" ::: "memory");
;     }
;     __syncthreads();
; }
; __global__ void __launch_bounds__(512, 2) mk_fwd(Args a) {
;     ...
;     GSYNC();
.LBB0_255:
	s_waitcnt vmcnt(0)
	v_readlane_b32 s4, v255, 0
	v_readlane_b32 s5, v255, 1
	s_barrier
	s_and_saveexec_b64 s[0:1], s[4:5]
	s_xor_b64 s[4:5], exec, s[0:1]
	s_cbranch_execz .LBB0_272
	s_getreg_b32 s6, hwreg(HW_REG_XCC_ID, 0, 4)
	s_and_b32 s6, s6, 7
	s_lshl_b32 s6, s6, 8
	s_add_i32 s7, s6, 0x16000
	v_mov_b32_e32 v0, s7
	v_mov_b32_e32 v1, 1
	global_atomic_add v1, v0, v1, s[22:23] sc0
	s_waitcnt vmcnt(0)
	v_readfirstlane_b32 s7, v1
	s_nop 1
	s_add_i32 s7, s7, 1
	s_cmp_lg_u32 s7, 96
	s_cbranch_scc1 .Lmy_gb3_follow
	buffer_wbl2 sc1
	s_waitcnt vmcnt(0)
	v_mov_b32_e32 v0, 0x18000
	v_mov_b32_e32 v1, 1
	global_atomic_add v1, v0, v1, s[22:23] sc0
	s_waitcnt vmcnt(0)
	v_readfirstlane_b32 s7, v1
	s_nop 1
	s_add_i32 s7, s7, 1
	v_mov_b32_e32 v0, 0x18100
	s_cmp_lg_u32 s7, 24
	s_cbranch_scc1 .Lmy_gb3_topwait
	v_mov_b32_e32 v1, 1
	global_atomic_add v0, v1, s[22:23]
	s_branch .Lmy_gb3_rel

; __device__ __forceinline__ void grid_barrier(unsigned* ctr, unsigned target) {
;     ...
;         while (__hip_atomic_load(ctr, __ATOMIC_RELAXED, __HIP_MEMORY_SCOPE_AGENT) < target) { __builtin_amdgcn_s_sleep(2); if (++spins > (1u << 24)) break; }
;         __builtin_amdgcn_fence(__ATOMIC_ACQUIRE, "agent");
.Lmy_gb3_topspin:
	global_load_dword v1, v0, s[22:23] sc1
	s_waitcnt vmcnt(0)
	v_readfirstlane_b32 s7, v1
	s_nop 1
	s_cmp_ge_u32 s7, 3
	s_cbranch_scc1 .Lmy_gb3_rel
	s_sleep 1
	s_add_i32 s8, s8, -1
	s_cmp_lg_u32 s8, 0
	s_cbranch_scc1 .Lmy_gb3_topspin

; __global__ void __launch_bounds__(512, 2) mk_fwd(Args a) {
;     ...
;     for (int repb = 0; repb < REP_P2B; ++repb)
;     for (unsigned idx = (unsigned)bx * 512u + (unsigned)threadIdx.x; idx < (unsigned)TT * 32u; idx += (unsigned)G * 512u) {
;         const size_t tok = idx >> 5; const int part = (int)(idx & 31u), hh = part >> 3;
;         const float l0 = LSE[tok * 4 + hh], l1 = LSE[((size_t)TT + tok) * 4 + hh], l2 = LSE[((size_t)2 * TT + tok) * 4 + hh];
;         const float mx = fmaxf(l0, fmaxf(l1, l2)); float w0 = __builtin_amdgcn_exp2f(l0 - mx), w1 = __builtin_amdgcn_exp2f(l1 - mx), w2 = __builtin_amdgcn_exp2f(l2 - mx);
;         const float inv = 1.f / (w0 + w1 + w2); w0 *= inv; w1 *= inv; w2 *= inv;
.Lmy_gb3_done:
.LBB0_272:
	s_or_b64 exec, exec, s[4:5]
	v_lshl_add_u32 v8, s2, 9, v254
	s_mov_b32 s0, 0x280000
	v_cmp_gt_u32_e32 vcc, s0, v8
	s_barrier
	s_and_saveexec_b64 s[2:3], vcc
	s_cbranch_execz .LBB0_275
	v_lshrrev_b32_e32 v0, 1, v254
	v_and_b32_e32 v4, 31, v254
	v_and_b32_e32 v0, 12, v0
	v_mov_b32_e32 v1, 0
	v_lshl_add_u64 v[2:3], s[14:15], 0, v[0:1]
	v_lshlrev_b32_e32 v0, 3, v4
	v_lshlrev_b32_e32 v4, 4, v4
	v_mov_b32_e32 v5, v1
	s_lshl_b32 s7, s24, 9
	v_lshl_add_u64 v[4:5], s[20:21], 0, v[4:5]
	v_lshl_add_u64 v[6:7], s[16:17], 0, v[0:1]
	s_mov_b64 s[4:5], 0
	s_mov_b32 s6, 0x41000000
	s_movk_i32 s8, 0x300
	s_mov_b32 s9, 0x27ffff

; #define GSYNC() do { ++bar_n; grid_barrier(bar_ctr, bar_n * (unsigned)G); } while (0)
; __device__ __forceinline__ void grid_barrier(unsigned* ctr, unsigned target) {
;     asm volatile("s_waitcnt vmcnt(0)" ::: "memory");
;     __syncthreads();
;     if (threadIdx.x == 0) {
;         __builtin_amdgcn_fence(__ATOMIC_RELEASE, "agent");
;         asm volatile("s_waitcnt vmcnt(0)" ::: "memory");
;         __hip_atomic_fetch_add(ctr, 1u, __ATOMIC_RELAXED, __HIP_MEMORY_SCOPE_AGENT);
;         unsigned spins = 0;
;         while (__hip_atomic_load(ctr, __ATOMIC_RELAXED, __HIP_MEMORY_SCOPE_AGENT) < target) { __builtin_amdgcn_s_sleep(2); if (++spins > (1u << 24)) break; }
;         __builtin_amdgcn_fence(__ATOMIC_ACQUIRE, "agent");
;         asm volatile("s_waitcnt vmcnt(0)" ::: "memory");
;     }
;     __syncthreads();
; }
; __global__ void __launch_bounds__(512, 2) mk_fwd(Args a) {
;     ...
;     GSYNC();
.LBB0_275:
	s_or_b64 exec, exec, s[2:3]
	s_waitcnt vmcnt(0)
	s_barrier
	s_mov_b64 s[2:3], exec
	v_readlane_b32 s0, v255, 0
	v_readlane_b32 s1, v255, 1
	s_and_b64 s[0:1], s[2:3], s[0:1]
	s_mov_b64 exec, s[0:1]
	s_cbranch_execz .LBB0_292
	s_getreg_b32 s4, hwreg(HW_REG_XCC_ID, 0, 4)
	s_and_b32 s4, s4, 7
	s_lshl_b32 s4, s4, 8
	s_add_i32 s5, s4, 0x16000
	v_mov_b32_e32 v0, s5
	v_mov_b32_e32 v1, 1
	global_atomic_add v1, v0, v1, s[22:23] sc0
	s_waitcnt vmcnt(0)
	v_readfirstlane_b32 s5, v1
	s_nop 1
	s_add_i32 s5, s5, 1
	s_cmp_lg_u32 s5, 128
	s_cbranch_scc1 .Lmy_gb4_follow
	buffer_wbl2 sc1
	s_waitcnt vmcnt(0)
	v_mov_b32_e32 v0, 0x18000
	v_mov_b32_e32 v1, 1
	global_atomic_add v1, v0, v1, s[22:23] sc0
	s_waitcnt vmcnt(0)
	v_readfirstlane_b32 s5, v1
	s_nop 1
	s_add_i32 s5, s5, 1
	v_mov_b32_e32 v0, 0x18100
	s_cmp_lg_u32 s5, 32
	s_cbranch_scc1 .Lmy_gb4_topwait
	v_mov_b32_e32 v1, 1
	global_atomic_add v0, v1, s[22:23]
	s_branch .Lmy_gb4_rel
.Lmy_gb4_topwait:
	s_mov_b32 s6, 0x400000
.Lmy_gb4_topspin:
	global_load_dword v1, v0, s[22:23] sc1
	s_waitcnt vmcnt(0)
	v_readfirstlane_b32 s5, v1
	s_nop 1
	s_cmp_ge_u32 s5, 4
	s_cbranch_scc1 .Lmy_gb4_rel
	s_sleep 1
	s_add_i32 s6, s6, -1
	s_cmp_lg_u32 s6, 0
	s_cbranch_scc1 .Lmy_gb4_topspin
.Lmy_gb4_rel:
	buffer_inv sc1
	s_add_i32 s5, s4, 0x17000
	v_mov_b32_e32 v0, s5
	v_mov_b32_e32 v1, 1
	global_atomic_add v0, v1, s[22:23]
	s_waitcnt vmcnt(0)
	s_branch .Lmy_gb4_done
.Lmy_gb4_follow:
	s_add_i32 s5, s4, 0x17000
	v_mov_b32_e32 v0, s5
	s_mov_b32 s6, 0x400000

; #define PG8_WAIT_V(n) asm volatile("s_waitcnt vmcnt(" #n ")" ::: "memory")
; #define PG8_BAR __builtin_amdgcn_s_barrier()
; template <class Epi, class Sched, bool ALIGN_EPI = false, bool SP2 = false, bool FP8 = false>
; __device__ __forceinline__ void gemm_phase(PG8_LAS unsigned char* lds, const Gemm g, const Sched& S, const Epi& E) {
;     ...
;     const int tid = tid_l, wid = __builtin_amdgcn_readfirstlane(tid >> 6), lane = tid & 63, wr = wid >> 2, wc = wid & 3, fr = lane & 15, fq = lane >> 4;
;     const int K = g.K, nt = K / BK;
;     unsigned voffA[2], voffB[2];
; #pragma unroll
;     for (int i = 0; i < 2; ++i) { int R, C; stage_rc(tid * 16 + i * 8192, R, C); const int Rb = Epi::PERM ? ((R & ~31) + perm32(R & 31)) : R;
;         voffA[i] = (unsigned)(R * K + C) * 2u; voffB[i] = (unsigned)(Rb * K + C) * 2u; }
;     const size_t kstep = (size_t)(BK * 2);
;     const size_t hstep = (size_t)HALF * K * 2;
;     const size_t tstep = 2 * hstep;
;     const unsigned ldsw = (unsigned)wid * 1024u;
;     const int aoff = lds_byte(wr * 64 + fr, fq * 8), boff = lds_byte(wc * 32 + fr, fq * 8);
;     ...
;     Unit cur, nxt; int ui = 0;
;     if (!S.next(0, cur)) return;
;     f32x4 acc[2][2][4][2];
; #pragma unroll
;     for (int a = 0; a < 2; ++a)
; #pragma unroll
;         for (int b = 0; b < 2; ++b)
; #pragma unroll
;             for (int m = 0; m < 4; ++m)
; #pragma unroll
;                 for (int n = 0; n < 2; ++n) { acc[a][b][m][n] = (f32x4){0.f, 0.f, 0.f, 0.f}; if constexpr (FP8) asm volatile("" : "+v"(acc[a][b][m][n])); }
;     bf16x8 At[4][2], B0[2][2], B1[2][2];
;     typedef int v4i_t __attribute__((ext_vector_type(4))); typedef int v8i_t __attribute__((ext_vector_type(8)));
;     const char* cA = (const char*)g.A + (size_t)cur.pm * tstep; const char* cB = (const char*)g.Bt + (size_t)cur.pn * tstep;
;     S.a_ready(cur);
;     if constexpr (SP2) {
;         PG8_STAGE(PG8_SB(0, 0), cB, voffB); PG8_STAGE(PG8_SB(0, 1), cB + hstep, voffB); PG8_STAGE(PG8_SA(0, 0), cA, voffA); PG8_STAGE(PG8_SA(0, 1), cA + hstep, voffA);
;         if (wr == 1) PG8_BAR;
;         PG8_WAIT_V(2); PG8_BAR;
; __global__ void __launch_bounds__(512, 2) mk_fwd(Args a) {
;     ...
;     { pg8::Gemm g{OA, Wa_t, TT, DM, 768 / 2}; pg8::StaticOrder S; S.init(TT, DM, G, vbx); pg8::EpiGate2 E{MRG, (const unsigned char*)Gt};
;       pg8::gemm_phase<pg8::EpiGate2, pg8::StaticOrder, true, true, true>(lds, g, S, E); }
.Lmy_gb4_done:
.LBB0_292:
	s_or_b64 exec, exec, s[2:3]
	v_mov_b32_e32 v130, v254
	s_cmpk_lt_i32 s33, 0x500
	s_barrier
	s_cselect_b64 s[6:7], -1, 0
	s_cmpk_gt_i32 s33, 0x4ff
	v_readfirstlane_b32 s2, v130
	s_cbranch_scc1 .LBB0_314
	v_bfe_i32 v2, v130, 27, 1
	v_lshlrev_b32_e32 v0, 4, v130
	v_lshrrev_b32_e32 v2, 22, v2
	v_add_u32_e32 v2, v0, v2
	v_and_b32_e32 v2, 0xfffffc00, v2
	v_sub_u32_e32 v2, v0, v2
	v_lshrrev_b32_e32 v3, 4, v2
	v_ashrrev_i32_e32 v1, 31, v130
	v_bitop3_b32 v2, v3, v2, 32 bitop3:0x6c
	v_lshrrev_b32_e32 v1, 26, v1
	v_ashrrev_i32_e32 v4, 31, v2
	v_add_u32_e32 v1, v130, v1
	v_lshrrev_b32_e32 v4, 26, v4
	v_ashrrev_i32_e32 v1, 6, v1
	v_add_u32_e32 v4, v2, v4
	v_lshlrev_b32_e32 v3, 3, v1
	v_ashrrev_i32_e32 v5, 6, v4
	v_and_b32_e32 v4, 0xc0, v4
	v_and_b32_e32 v3, -16, v3
	v_lshlrev_b32_e32 v1, 5, v1
	v_sub_u32_e32 v2, v2, v4
	v_mov_b32_e32 v4, 1
	v_add_u32_e32 v3, v5, v3
	v_and_b32_e32 v1, 32, v1
	v_ashrrev_i16_sdwa v2, v4, sext(v2) dst_sel:DWORD dst_unused:UNUSED_PAD src0_sel:DWORD src1_sel:BYTE_0
	v_add_u32_sdwa v1, v1, sext(v2) dst_sel:DWORD dst_unused:UNUSED_PAD src0_sel:DWORD src1_sel:WORD_0
	v_lshlrev_b32_e32 v2, 1, v3
	v_lshrrev_b32_e32 v6, 2, v3
	v_and_b32_e32 v5, 3, v5
	s_mov_b32 s0, 0x1ffffe0
	v_and_b32_e32 v2, 24, v2
	v_and_b32_e32 v6, 4, v6
	v_and_or_b32 v5, v3, s0, v5
	v_or3_b32 v2, v5, v6, v2
	s_movk_i32 s1, 0x180
	v_mul_lo_u32 v3, v3, s1
	v_mul_lo_u32 v2, v2, s1
	v_add_u32_e32 v0, 0x2000, v0
	v_add_lshl_u32 v146, v1, v3, 1
	v_add_lshl_u32 v147, v2, v1, 1
	v_ashrrev_i32_e32 v1, 31, v0
	v_lshrrev_b32_e32 v1, 22, v1
	v_add_u32_e32 v1, v0, v1
	v_ashrrev_i32_e32 v1, 10, v1
	v_mul_i32_i24_e32 v2, 0x400, v1
	v_sub_u32_e32 v0, v0, v2
	v_lshrrev_b32_e32 v2, 4, v0
	v_bitop3_b32 v0, v2, v0, 32 bitop3:0x6c
	v_ashrrev_i32_e32 v3, 31, v0
	v_lshrrev_b32_e32 v3, 26, v3
	v_add_u32_e32 v3, v0, v3
	v_lshlrev_b32_e32 v2, 3, v1
	v_ashrrev_i32_e32 v5, 6, v3
	v_and_b32_e32 v3, 0xc0, v3
	v_and_b32_e32 v2, -16, v2
	v_lshlrev_b32_e32 v1, 5, v1
	v_sub_u32_e32 v0, v0, v3
	v_add_u32_e32 v2, v5, v2
	v_and_b32_e32 v1, 32, v1
	v_ashrrev_i16_sdwa v0, v4, sext(v0) dst_sel:DWORD dst_unused:UNUSED_PAD src0_sel:DWORD src1_sel:BYTE_0
	v_add_u32_sdwa v0, v1, sext(v0) dst_sel:DWORD dst_unused:UNUSED_PAD src0_sel:DWORD src1_sel:WORD_0
	v_lshlrev_b32_e32 v1, 1, v2
	v_lshrrev_b32_e32 v3, 2, v2
	v_and_b32_e32 v4, 3, v5
	v_and_b32_e32 v1, 24, v1
	v_and_b32_e32 v3, 4, v3
	v_and_or_b32 v4, v2, s0, v4
	s_lshr_b32 s0, s76, 29
	v_or3_b32 v1, v4, v3, v1
	s_add_i32 s0, s33, s0
	v_mul_lo_u32 v2, v2, s1
	v_mul_lo_u32 v1, v1, s1
	s_ashr_i32 s5, s2, 6
	s_ashr_i32 s1, s0, 3
	s_and_b32 s0, s0, -8
	s_ashr_i32 s3, s2, 8
	s_lshl_b32 s66, s5, 10
	s_sub_i32 s0, s33, s0
	s_cmp_lt_i32 s0, 0
	s_movk_i32 s67, 0xa1
	s_cselect_b32 s4, s67, 0xa0
	s_mul_i32 s0, s0, s4
	s_add_i32 s0, s0, s1
	s_ashr_i32 s1, s0, 31
	s_lshr_b32 s1, s1, 27
	s_add_i32 s1, s0, s1
	s_ashr_i32 s4, s1, 5
	s_and_b32 s1, s1, 0xffe0
	s_sub_i32 s0, s0, s1
	s_bfe_i32 s1, s0, 0x80000
	s_bfe_u32 s1, s1, 0x3000c
	s_add_i32 s1, s0, s1
	s_lshl_b32 s9, s4, 3
	s_bfe_i32 s4, s1, 0x80000
	s_and_b32 s1, s1, 0xf8
	s_sub_i32 s0, s0, s1
	s_sext_i32_i16 s12, s4
	s_sext_i32_i8 s0, s0
	s_mov_b32 s8, 0
	s_add_i32 s64, s9, s0
	s_ashr_i32 s0, s12, 3
	s_lshr_b32 s4, s12, 3
	s_mov_b32 s9, s8
	s_mov_b32 s10, s8
	s_mov_b32 s11, s8
	s_mul_hi_i32 s1, s0, 0x30000
	s_mul_i32 s0, s0, 0x30000
	v_readlane_b32 s12, v255, 2
	v_add_lshl_u32 v148, v0, v2, 1
	v_add_lshl_u32 v149, v1, v0, 1
	v_mov_b64_e32 v[0:1], s[8:9]
	v_mov_b64_e32 v[114:115], s[10:11]
	v_mov_b64_e32 v[118:119], s[10:11]
	s_waitcnt vmcnt(0)
	v_mov_b64_e32 v[98:99], s[10:11]
	v_mov_b64_e32 v[102:103], s[10:11]
	v_mov_b64_e32 v[82:83], s[10:11]
	v_mov_b64_e32 v[86:87], s[10:11]
	v_mov_b64_e32 v[66:67], s[10:11]
	v_mov_b64_e32 v[70:71], s[10:11]
	v_mov_b64_e32 v[122:123], s[10:11]
	v_mov_b64_e32 v[126:127], s[10:11]
	v_mov_b64_e32 v[106:107], s[10:11]
	v_mov_b64_e32 v[110:111], s[10:11]
	v_mov_b64_e32 v[90:91], s[10:11]
	v_mov_b64_e32 v[94:95], s[10:11]
	v_mov_b64_e32 v[74:75], s[10:11]
	v_mov_b64_e32 v[78:79], s[10:11]
	v_mov_b64_e32 v[50:51], s[10:11]
	v_mov_b64_e32 v[54:55], s[10:11]
	v_mov_b64_e32 v[34:35], s[10:11]
	v_mov_b64_e32 v[38:39], s[10:11]
	v_mov_b64_e32 v[18:19], s[10:11]
	v_mov_b64_e32 v[22:23], s[10:11]
	v_mov_b64_e32 v[4:5], s[8:9]
	v_mov_b64_e32 v[8:9], s[8:9]
	v_mov_b64_e32 v[58:59], s[10:11]
	v_mov_b64_e32 v[62:63], s[10:11]
	v_mov_b64_e32 v[42:43], s[10:11]
	v_mov_b64_e32 v[46:47], s[10:11]
	v_mov_b64_e32 v[26:27], s[10:11]
	v_mov_b64_e32 v[30:31], s[10:11]
	v_mov_b64_e32 v[14:15], s[10:11]
	v_readlane_b32 s13, v255, 3
	s_add_u32 s62, s12, s0
	v_mov_b64_e32 v[2:3], s[10:11]
	v_mov_b64_e32 v[112:113], s[8:9]
	v_mov_b64_e32 v[116:117], s[8:9]
	v_mov_b64_e32 v[96:97], s[8:9]
	v_mov_b64_e32 v[100:101], s[8:9]
	v_mov_b64_e32 v[80:81], s[8:9]
	v_mov_b64_e32 v[84:85], s[8:9]
	v_mov_b64_e32 v[64:65], s[8:9]
	v_mov_b64_e32 v[68:69], s[8:9]
	v_mov_b64_e32 v[120:121], s[8:9]
	v_mov_b64_e32 v[124:125], s[8:9]
	v_mov_b64_e32 v[104:105], s[8:9]
	v_mov_b64_e32 v[108:109], s[8:9]
	v_mov_b64_e32 v[88:89], s[8:9]
	v_mov_b64_e32 v[92:93], s[8:9]
	v_mov_b64_e32 v[72:73], s[8:9]
	v_mov_b64_e32 v[76:77], s[8:9]
	v_mov_b64_e32 v[48:49], s[8:9]
	v_mov_b64_e32 v[52:53], s[8:9]
	v_mov_b64_e32 v[32:33], s[8:9]
	v_mov_b64_e32 v[36:37], s[8:9]
	v_mov_b64_e32 v[16:17], s[8:9]
	v_mov_b64_e32 v[20:21], s[8:9]
	v_mov_b64_e32 v[6:7], s[10:11]
	v_mov_b64_e32 v[10:11], s[10:11]
	v_mov_b64_e32 v[56:57], s[8:9]
	v_mov_b64_e32 v[60:61], s[8:9]
	v_mov_b64_e32 v[40:41], s[8:9]
	v_mov_b64_e32 v[44:45], s[8:9]
	v_mov_b64_e32 v[24:25], s[8:9]
	v_mov_b64_e32 v[28:29], s[8:9]
	v_mov_b64_e32 v[12:13], s[8:9]
	s_addc_u32 s63, s13, s1
	s_add_i32 s68, s66, 0
	v_mov_b32_e32 v128, v147
	s_add_i32 m0, s68, 0x10000
	s_mul_i32 s10, s64, 0x30000
	global_load_lds_dwordx4 v128, s[62:63]
	v_mov_b32_e32 v128, v149
	s_add_i32 m0, s68, 0x12000
	s_add_u32 s0, s62, 0x18000
	global_load_lds_dwordx4 v128, s[62:63]
	v_mov_b32_e32 v128, v147
	s_addc_u32 s1, s63, 0
	s_add_i32 m0, s68, 0x14000
	s_mul_hi_i32 s9, s64, 0x30000
	global_load_lds_dwordx4 v128, s[0:1]
	v_mov_b32_e32 v128, v149
	s_add_i32 m0, s68, 0x16000
	s_add_u32 s10, s16, s10
	global_load_lds_dwordx4 v128, s[0:1]
	v_mov_b32_e32 v128, v146
	s_addc_u32 s11, s17, s9
	s_mov_b32 m0, s68
	s_add_i32 s69, s68, 0x2000
	global_load_lds_dwordx4 v128, s[10:11]
	v_mov_b32_e32 v128, v148
	s_mov_b32 m0, s69
	s_add_u32 s0, s10, 0x18000
	global_load_lds_dwordx4 v128, s[10:11]
	s_addc_u32 s1, s11, 0
	s_add_i32 s70, s68, 0x4000
	v_mov_b32_e32 v128, v146
	s_mov_b32 m0, s70
	s_add_i32 s71, s68, 0x6000
	global_load_lds_dwordx4 v128, s[0:1]
	v_mov_b32_e32 v128, v148
	s_mov_b32 m0, s71
	s_cmp_eq_u32 s3, 1
	global_load_lds_dwordx4 v128, s[0:1]
	s_mov_b32 s72, 0x10000
	s_cselect_b64 s[12:13], -1, 0
	s_cmp_lg_u32 s3, 1
	s_mov_b64 s[14:15], 0x18000
	s_cbranch_scc1 .LBB0_295
	s_barrier

; #define GSYNC() do { ++bar_n; grid_barrier(bar_ctr, bar_n * (unsigned)G); } while (0)
; __device__ __forceinline__ void grid_barrier(unsigned* ctr, unsigned target) {
;     asm volatile("s_waitcnt vmcnt(0)" ::: "memory");
;     __syncthreads();
;     if (threadIdx.x == 0) {
;         __builtin_amdgcn_fence(__ATOMIC_RELEASE, "agent");
;         asm volatile("s_waitcnt vmcnt(0)" ::: "memory");
;         __hip_atomic_fetch_add(ctr, 1u, __ATOMIC_RELAXED, __HIP_MEMORY_SCOPE_AGENT);
;         unsigned spins = 0;
;         while (__hip_atomic_load(ctr, __ATOMIC_RELAXED, __HIP_MEMORY_SCOPE_AGENT) < target) { __builtin_amdgcn_s_sleep(2); if (++spins > (1u << 24)) break; }
;         __builtin_amdgcn_fence(__ATOMIC_ACQUIRE, "agent");
;         asm volatile("s_waitcnt vmcnt(0)" ::: "memory");
;     }
;     __syncthreads();
; }
; __global__ void __launch_bounds__(512, 2) mk_fwd(Args a) {
;     ...
;     GSYNC();
.LBB0_314:
	s_waitcnt vmcnt(0)
	s_barrier
	s_mov_b64 s[2:3], exec
	v_readlane_b32 s0, v255, 0
	v_readlane_b32 s1, v255, 1
	s_and_b64 s[0:1], s[2:3], s[0:1]
	s_mov_b64 exec, s[0:1]
	s_cbranch_execz .LBB0_331
	s_getreg_b32 s4, hwreg(HW_REG_XCC_ID, 0, 4)
	s_and_b32 s4, s4, 7
	s_lshl_b32 s4, s4, 8
	s_add_i32 s5, s4, 0x16000
	v_mov_b32_e32 v0, s5
	v_mov_b32_e32 v1, 1
	global_atomic_add v1, v0, v1, s[22:23] sc0
	s_waitcnt vmcnt(0)
	v_readfirstlane_b32 s5, v1
	s_nop 1
	s_add_i32 s5, s5, 1
	s_cmp_lg_u32 s5, 160
	s_cbranch_scc1 .Lmy_gb5_follow
	buffer_wbl2 sc1
	s_waitcnt vmcnt(0)
	v_mov_b32_e32 v0, 0x18000
	v_mov_b32_e32 v1, 1
	global_atomic_add v1, v0, v1, s[22:23] sc0
	s_waitcnt vmcnt(0)
	v_readfirstlane_b32 s5, v1
	s_nop 1
	s_add_i32 s5, s5, 1
	v_mov_b32_e32 v0, 0x18100
	s_cmp_lg_u32 s5, 40
	s_cbranch_scc1 .Lmy_gb5_topwait
	v_mov_b32_e32 v1, 1
	global_atomic_add v0, v1, s[22:23]
	s_branch .Lmy_gb5_rel

; __device__ __forceinline__ void grid_barrier(unsigned* ctr, unsigned target) {
;     ...
;         while (__hip_atomic_load(ctr, __ATOMIC_RELAXED, __HIP_MEMORY_SCOPE_AGENT) < target) { __builtin_amdgcn_s_sleep(2); if (++spins > (1u << 24)) break; }
;         __builtin_amdgcn_fence(__ATOMIC_ACQUIRE, "agent");
.Lmy_gb5_topspin:
	global_load_dword v1, v0, s[22:23] sc1
	s_waitcnt vmcnt(0)
	v_readfirstlane_b32 s5, v1
	s_nop 1
	s_cmp_ge_u32 s5, 5
	s_cbranch_scc1 .Lmy_gb5_rel
	s_sleep 1
	s_add_i32 s8, s8, -1
	s_cmp_lg_u32 s8, 0
	s_cbranch_scc1 .Lmy_gb5_topspin

; __device__ __forceinline__ void grid_barrier(unsigned* ctr, unsigned target) {
;     ...
;         while (__hip_atomic_load(ctr, __ATOMIC_RELAXED, __HIP_MEMORY_SCOPE_AGENT) < target) { __builtin_amdgcn_s_sleep(2); if (++spins > (1u << 24)) break; }
.Lmy_gb5_follow:
	s_add_i32 s5, s4, 0x17000
	v_mov_b32_e32 v0, s5
	s_mov_b32 s8, 0x400000

;     __host__ __device__ bool next(int i, Unit& u) const {
;         const long L = (long)i * G + c; if (L >= nwg) return false;
;         int wgid = (int)L; { const int q = nwg / NXCD, r = nwg % NXCD, xcd = wgid % NXCD, off = wgid / NXCD; wgid = (xcd < r ? xcd * (q + 1) : r * (q + 1) + (xcd - r) * q) + off; }
;         const int nig = WGM * nN, gid = wgid / nig, fm = gid * WGM, gsz = (nM - fm) < WGM ? (nM - fm) : WGM;
;         u.pm = fm + ((wgid % nig) % gsz); u.pn = (wgid % nig) / gsz; return true;
; __global__ void __launch_bounds__(512, 2) mk_fwd(Args a) {
;     ...
;     for (int rep = 0; rep < REP_P4; ++rep) { pg8::Gemm g{MRG, Wout_t, TT, DM, DM / 2}; pg8::StaticOrder S; S.init(TT, DM, G, vbx); pg8::EpiRes<true> E{x_p, x_s, out, X1B, SSQ1, 1.f / 512.f};
.Lmy_gb5_done:
.LBB0_331:
	s_or_b64 exec, exec, s[2:3]
	v_mov_b32_e32 v128, v254
	s_barrier
	s_and_b64 vcc, exec, s[6:7]
	v_readfirstlane_b32 s4, v128
	s_cbranch_vccz .LBB0_333
	s_lshr_b32 s0, s76, 29
	s_add_i32 s0, s33, s0
	s_ashr_i32 s1, s0, 3
	s_and_b32 s0, s0, -8
	s_sub_i32 s0, s33, s0
	s_cmp_lt_i32 s0, 0
	s_movk_i32 s2, 0xa1
	s_cselect_b32 s2, s2, 0xa0
	s_mul_i32 s0, s0, s2
	s_add_i32 s0, s0, s1
	s_ashr_i32 s1, s0, 31
	s_lshr_b32 s1, s1, 27
	s_add_i32 s1, s0, s1
	s_ashr_i32 s2, s1, 5
	s_and_b32 s1, s1, 0xffe0
	s_sub_i32 s0, s0, s1
	s_bfe_i32 s1, s0, 0x80000
	s_bfe_u32 s1, s1, 0x3000c
	s_add_i32 s1, s0, s1
	s_bfe_i32 s3, s1, 0x80000
	s_and_b32 s1, s1, 0xf8
	s_sub_i32 s0, s0, s1
	s_lshl_b32 s2, s2, 3
	s_sext_i32_i16 s3, s3
	s_sext_i32_i8 s0, s0
	s_add_i32 s52, s2, s0
	s_ashr_i32 s50, s3, 3

; #define GSYNC() do { ++bar_n; grid_barrier(bar_ctr, bar_n * (unsigned)G); } while (0)
; __device__ __forceinline__ void grid_barrier(unsigned* ctr, unsigned target) {
;     asm volatile("s_waitcnt vmcnt(0)" ::: "memory");
;     __syncthreads();
;     if (threadIdx.x == 0) {
;         __builtin_amdgcn_fence(__ATOMIC_RELEASE, "agent");
;         asm volatile("s_waitcnt vmcnt(0)" ::: "memory");
;         __hip_atomic_fetch_add(ctr, 1u, __ATOMIC_RELAXED, __HIP_MEMORY_SCOPE_AGENT);
;         unsigned spins = 0;
;         while (__hip_atomic_load(ctr, __ATOMIC_RELAXED, __HIP_MEMORY_SCOPE_AGENT) < target) { __builtin_amdgcn_s_sleep(2); if (++spins > (1u << 24)) break; }
;         __builtin_amdgcn_fence(__ATOMIC_ACQUIRE, "agent");
;         asm volatile("s_waitcnt vmcnt(0)" ::: "memory");
;     }
;     __syncthreads();
; }
; __global__ void __launch_bounds__(512, 2) mk_fwd(Args a) {
;     ...
;     GSYNC();
.LBB0_365:
	s_waitcnt vmcnt(0)
	v_readlane_b32 s4, v255, 0
	v_readlane_b32 s5, v255, 1
	s_waitcnt lgkmcnt(0)
	s_barrier
	s_and_saveexec_b64 s[0:1], s[4:5]
	s_xor_b64 s[4:5], exec, s[0:1]
	s_cbranch_execz .LBB0_382
	s_getreg_b32 s6, hwreg(HW_REG_XCC_ID, 0, 4)
	s_and_b32 s6, s6, 7
	s_lshl_b32 s6, s6, 8
	s_add_i32 s7, s6, 0x16000
	v_mov_b32_e32 v0, s7
	v_mov_b32_e32 v1, 1
	global_atomic_add v1, v0, v1, s[22:23] sc0
	s_waitcnt vmcnt(0)
	v_readfirstlane_b32 s7, v1
	s_nop 1
	s_add_i32 s7, s7, 1
	s_cmp_lg_u32 s7, 192
	s_cbranch_scc1 .Lmy_gb6_follow
	buffer_wbl2 sc1
	s_waitcnt vmcnt(0)
	v_mov_b32_e32 v0, 0x18000
	v_mov_b32_e32 v1, 1
	global_atomic_add v1, v0, v1, s[22:23] sc0
	s_waitcnt vmcnt(0)
	v_readfirstlane_b32 s7, v1
	s_nop 1
	s_add_i32 s7, s7, 1
	v_mov_b32_e32 v0, 0x18100
	s_cmp_lg_u32 s7, 48
	s_cbranch_scc1 .Lmy_gb6_topwait
	v_mov_b32_e32 v1, 1
	global_atomic_add v0, v1, s[22:23]
	s_branch .Lmy_gb6_rel

; __device__ __forceinline__ void grid_barrier(unsigned* ctr, unsigned target) {
;     ...
;         while (__hip_atomic_load(ctr, __ATOMIC_RELAXED, __HIP_MEMORY_SCOPE_AGENT) < target) { __builtin_amdgcn_s_sleep(2); if (++spins > (1u << 24)) break; }
;         __builtin_amdgcn_fence(__ATOMIC_ACQUIRE, "agent");
.Lmy_gb6_topspin:
	global_load_dword v1, v0, s[22:23] sc1
	s_waitcnt vmcnt(0)
	v_readfirstlane_b32 s7, v1
	s_nop 1
	s_cmp_ge_u32 s7, 6
	s_cbranch_scc1 .Lmy_gb6_rel
	s_sleep 1
	s_add_i32 s8, s8, -1
	s_cmp_lg_u32 s8, 0
	s_cbranch_scc1 .Lmy_gb6_topspin

; #define PG8_WAIT_V(n) asm volatile("s_waitcnt vmcnt(" #n ")" ::: "memory")
; template <class Epi, class Sched, bool ALIGN_EPI = false, bool SP2 = false, bool FP8 = false>
; __device__ __forceinline__ void gemm_phase(PG8_LAS unsigned char* lds, const Gemm g, const Sched& S, const Epi& E) {
;     ...
;     const int tid = tid_l, wid = __builtin_amdgcn_readfirstlane(tid >> 6), lane = tid & 63, wr = wid >> 2, wc = wid & 3, fr = lane & 15, fq = lane >> 4;
;     const int K = g.K, nt = K / BK;
;     unsigned voffA[2], voffB[2];
; #pragma unroll
;     for (int i = 0; i < 2; ++i) { int R, C; stage_rc(tid * 16 + i * 8192, R, C); const int Rb = Epi::PERM ? ((R & ~31) + perm32(R & 31)) : R;
;         voffA[i] = (unsigned)(R * K + C) * 2u; voffB[i] = (unsigned)(Rb * K + C) * 2u; }
;     const size_t kstep = (size_t)(BK * 2);
;     const size_t hstep = (size_t)HALF * K * 2;
;     const size_t tstep = 2 * hstep;
;     const unsigned ldsw = (unsigned)wid * 1024u;
;     const int aoff = lds_byte(wr * 64 + fr, fq * 8), boff = lds_byte(wc * 32 + fr, fq * 8);
;     ...
;     Unit cur, nxt; int ui = 0;
;     if (!S.next(0, cur)) return;
;     f32x4 acc[2][2][4][2];
; #pragma unroll
;     for (int a = 0; a < 2; ++a)
; #pragma unroll
;         for (int b = 0; b < 2; ++b)
; #pragma unroll
;             for (int m = 0; m < 4; ++m)
; #pragma unroll
;                 for (int n = 0; n < 2; ++n) { acc[a][b][m][n] = (f32x4){0.f, 0.f, 0.f, 0.f}; if constexpr (FP8) asm volatile("" : "+v"(acc[a][b][m][n])); }
;     bf16x8 At[4][2], B0[2][2], B1[2][2];
;     typedef int v4i_t __attribute__((ext_vector_type(4))); typedef int v8i_t __attribute__((ext_vector_type(8)));
;     const char* cA = (const char*)g.A + (size_t)cur.pm * tstep; const char* cB = (const char*)g.Bt + (size_t)cur.pn * tstep;
;     S.a_ready(cur);
;     if constexpr (SP2) {
;         PG8_STAGE(PG8_SB(0, 0), cB, voffB); PG8_STAGE(PG8_SB(0, 1), cB + hstep, voffB); PG8_STAGE(PG8_SA(0, 0), cA, voffA); PG8_STAGE(PG8_SA(0, 1), cA + hstep, voffA);
;         if (wr == 1) PG8_BAR;
;         PG8_WAIT_V(2); PG8_BAR;
; __global__ void __launch_bounds__(512, 2) mk_fwd(Args a) {
;     ...
;     for (int rep = 0; rep < REP_P5; ++rep) { pg8::Gemm g{X1B, Wup_t, TT, DFF, DM}; pg8::StaticOrder S; S.init(TT, DFF, G, vbx); pg8::EpiUp E{Hb, SSQ1};
;       pg8::gemm_phase<pg8::EpiUp, pg8::StaticOrder, true, true>(lds, g, S, E); }
.Lmy_gb6_done:
.LBB0_382:
	s_or_b64 exec, exec, s[4:5]
	s_mov_b32 s101, -1
	v_mov_b32_e32 v10, v254
	s_barrier
	s_cmpk_lt_i32 s33, 0x1400
	s_nop 0
	v_readfirstlane_b32 s5, v10
	s_cbranch_scc0 .LBB0_398
	v_lshlrev_b32_e32 v0, 4, v10
	v_add_u32_e32 v1, 0x2000, v0
	v_ashrrev_i32_e32 v2, 31, v1
	v_lshrrev_b32_e32 v2, 22, v2
	v_add_u32_e32 v2, v1, v2
	v_ashrrev_i32_e32 v8, 10, v2
	v_mul_i32_i24_e32 v2, 0x400, v8
	v_sub_u32_e32 v1, v1, v2
	v_lshrrev_b32_e32 v2, 4, v1
	v_bitop3_b32 v1, v2, v1, 32 bitop3:0x6c
	v_ashrrev_i32_e32 v2, 31, v1
	v_lshrrev_b32_e32 v2, 26, v2
	v_add_u32_e32 v2, v1, v2
	v_lshlrev_b32_e32 v3, 3, v8
	v_ashrrev_i32_e32 v9, 6, v2
	v_and_b32_e32 v3, -16, v3
	v_add_u32_e32 v3, v9, v3
	v_and_b32_e32 v4, 3, v9
	s_mov_b32 s0, 0x1fffe0
	v_lshrrev_b32_e32 v5, 2, v3
	v_lshlrev_b32_e32 v6, 1, v3
	v_and_b32_e32 v2, 0xc0, v2
	v_and_or_b32 v4, v3, s0, v4
	v_and_b32_e32 v5, 4, v5
	v_and_b32_e32 v6, 24, v6
	v_sub_u32_e32 v1, v1, v2
	v_mov_b32_e32 v2, 1
	v_or3_b32 v4, v4, v5, v6
	v_lshlrev_b32_e32 v5, 5, v8
	v_ashrrev_i16_sdwa v1, v2, sext(v1) dst_sel:DWORD dst_unused:UNUSED_PAD src0_sel:DWORD src1_sel:BYTE_0
	v_and_b32_e32 v5, 32, v5
	v_bfe_i32 v11, v1, 0, 16
	v_add_lshl_u32 v1, v5, v11, 1
	v_lshl_add_u32 v128, v4, 11, v1
	v_lshl_add_u32 v130, v3, 11, v1
	v_bfe_i32 v1, v10, 27, 1
	v_lshrrev_b32_e32 v1, 22, v1
	v_add_u32_e32 v1, v0, v1
	v_and_b32_e32 v1, 0xfffffc00, v1
	v_sub_u32_e32 v0, v0, v1
	v_lshrrev_b32_e32 v1, 4, v0
	v_ashrrev_i32_e32 v3, 31, v10
	v_bitop3_b32 v0, v1, v0, 32 bitop3:0x6c
	v_lshrrev_b32_e32 v3, 26, v3
	v_ashrrev_i32_e32 v1, 31, v0
	v_add_u32_e32 v3, v10, v3
	v_lshrrev_b32_e32 v1, 26, v1
	v_ashrrev_i32_e32 v13, 6, v3
	v_add_u32_e32 v1, v0, v1
	v_lshlrev_b32_e32 v3, 3, v13
	v_ashrrev_i32_e32 v12, 6, v1
	v_and_b32_e32 v3, -16, v3
	v_add_u32_e32 v3, v12, v3
	v_and_b32_e32 v4, 3, v12
	v_and_or_b32 v4, v3, s0, v4
	s_ashr_i32 s0, s33, 31
	s_lshr_b32 s0, s0, 29
	s_add_i32 s0, s33, s0
	s_ashr_i32 s8, s5, 6
	s_ashr_i32 s1, s0, 3
	s_and_b32 s0, s0, -8
	s_ashr_i32 s10, s5, 8
	s_lshl_b32 s46, s8, 10
	s_sub_i32 s0, s33, s0
	s_cmp_lt_i32 s0, 0
	s_movk_i32 s47, 0x281
	s_cselect_b32 s4, s47, 0x280
	s_mul_i32 s0, s0, s4
	s_add_i32 s0, s0, s1
	s_ashr_i32 s1, s0, 31
	s_lshr_b32 s1, s1, 25
	s_add_i32 s1, s0, s1
	s_ashr_i32 s4, s1, 7
	s_and_b32 s1, s1, 0xff80
	s_sub_i32 s0, s0, s1
	s_bfe_i32 s1, s0, 0x80000
	s_bfe_u32 s1, s1, 0x3000c
	s_add_i32 s1, s0, s1
	s_lshl_b32 s6, s4, 3
	s_bfe_i32 s4, s1, 0x80000
	s_and_b32 s1, s1, 0xf8
	s_sub_i32 s0, s0, s1
	s_sext_i32_i16 s4, s4
	s_sext_i32_i8 s0, s0
	v_lshrrev_b32_e32 v5, 2, v3
	v_lshlrev_b32_e32 v6, 1, v3
	v_and_b32_e32 v1, 0xc0, v1
	s_lshr_b32 s4, s4, 3
	s_add_i32 s38, s6, s0
	v_and_b32_e32 v5, 4, v5
	v_and_b32_e32 v6, 24, v6
	v_sub_u32_e32 v0, v0, v1
	s_ashr_i32 s39, s38, 31
	s_bfe_i64 s[6:7], s[4:5], 0x100000
	v_or3_b32 v4, v4, v5, v6
	v_lshlrev_b32_e32 v5, 5, v13
	v_ashrrev_i16_sdwa v0, v2, sext(v0) dst_sel:DWORD dst_unused:UNUSED_PAD src0_sel:DWORD src1_sel:BYTE_0
	s_lshl_b64 s[0:1], s[38:39], 19
	s_lshl_b64 s[6:7], s[6:7], 19
	v_and_b32_e32 v5, 32, v5
	v_bfe_i32 v14, v0, 0, 16
	s_add_u32 s42, s30, s6
	v_add_lshl_u32 v0, v5, v14, 1
	s_addc_u32 s43, s31, s7
	s_add_i32 s39, s46, 0
	v_lshl_add_u32 v132, v4, 11, v0
	s_add_i32 m0, s39, 0x10000
	v_lshl_add_u32 v134, v3, 11, v0
	global_load_lds_dwordx4 v132, s[42:43]
	s_add_i32 m0, s39, 0x12000
	s_add_u32 s6, s42, 0x40000
	global_load_lds_dwordx4 v128, s[42:43]
	s_addc_u32 s7, s43, 0
	s_add_i32 m0, s39, 0x14000
	v_mov_b32_e32 v133, 0
	global_load_lds_dwordx4 v132, s[6:7]
	s_add_i32 m0, s39, 0x16000
	s_add_u32 s40, s16, s0
	s_addc_u32 s41, s17, s1
	s_add_i32 s48, s39, 0x2000
	global_load_lds_dwordx4 v128, s[6:7]
	s_mov_b32 m0, s39
	s_add_u32 s0, s40, 0x40000
	global_load_lds_dwordx4 v134, s[40:41]
	s_mov_b32 m0, s48
	s_addc_u32 s1, s41, 0
	s_add_i32 s49, s39, 0x4000
	global_load_lds_dwordx4 v130, s[40:41]
	s_mov_b32 m0, s49
	s_add_i32 s50, s39, 0x6000
	global_load_lds_dwordx4 v134, s[0:1]
	s_mov_b32 m0, s50
	v_mov_b32_e32 v129, v133
	global_load_lds_dwordx4 v130, s[0:1]
	v_mov_b32_e32 v135, v133
	v_mov_b32_e32 v131, v133
	s_cmp_eq_u32 s10, 1
	s_mov_b32 s51, 0
	v_lshl_add_u64 v[6:7], s[42:43], 0, v[132:133]
	v_lshl_add_u64 v[4:5], s[42:43], 0, v[128:129]
	v_lshl_add_u64 v[0:1], s[40:41], 0, v[134:135]
	s_cselect_b64 s[6:7], -1, 0
	s_cmp_lg_u32 s10, 1
	v_lshl_add_u64 v[2:3], s[40:41], 0, v[130:131]
	s_cbranch_scc1 .LBB0_385
	s_barrier

; #define GSYNC() do { ++bar_n; grid_barrier(bar_ctr, bar_n * (unsigned)G); } while (0)
; __device__ __forceinline__ void grid_barrier(unsigned* ctr, unsigned target) {
;     asm volatile("s_waitcnt vmcnt(0)" ::: "memory");
;     __syncthreads();
;     if (threadIdx.x == 0) {
;         __builtin_amdgcn_fence(__ATOMIC_RELEASE, "agent");
;         asm volatile("s_waitcnt vmcnt(0)" ::: "memory");
;         __hip_atomic_fetch_add(ctr, 1u, __ATOMIC_RELAXED, __HIP_MEMORY_SCOPE_AGENT);
;         unsigned spins = 0;
;         while (__hip_atomic_load(ctr, __ATOMIC_RELAXED, __HIP_MEMORY_SCOPE_AGENT) < target) { __builtin_amdgcn_s_sleep(2); if (++spins > (1u << 24)) break; }
;         __builtin_amdgcn_fence(__ATOMIC_ACQUIRE, "agent");
;         asm volatile("s_waitcnt vmcnt(0)" ::: "memory");
;     }
;     __syncthreads();
; }
; __global__ void __launch_bounds__(512, 2) mk_fwd(Args a) {
;     ...
;     GSYNC();
.LBB0_398:
	s_waitcnt vmcnt(0)
	s_barrier
	s_mov_b64 s[0:1], exec
	v_readlane_b32 s4, v255, 0
	v_readlane_b32 s5, v255, 1
	s_and_b64 s[4:5], s[0:1], s[4:5]
	s_xor_b64 s[0:1], s[4:5], s[0:1]
	s_mov_b64 exec, s[4:5]
	s_cbranch_execz .LBB0_415
	s_getreg_b32 s4, hwreg(HW_REG_XCC_ID, 0, 4)
	s_and_b32 s4, s4, 7
	s_lshl_b32 s4, s4, 8
	s_add_i32 s5, s4, 0x16000
	v_mov_b32_e32 v0, s5
	v_mov_b32_e32 v1, 1
	global_atomic_add v1, v0, v1, s[22:23] sc0
	s_waitcnt vmcnt(0)
	v_readfirstlane_b32 s5, v1
	s_nop 1
	s_add_i32 s5, s5, 1
	s_cmp_lg_u32 s5, 224
	s_cbranch_scc1 .Lmy_gb7_follow
	buffer_wbl2 sc1
	s_waitcnt vmcnt(0)
	v_mov_b32_e32 v0, 0x18000
	v_mov_b32_e32 v1, 1
	global_atomic_add v1, v0, v1, s[22:23] sc0
	s_waitcnt vmcnt(0)
	v_readfirstlane_b32 s5, v1
	s_nop 1
	s_add_i32 s5, s5, 1
	v_mov_b32_e32 v0, 0x18100
	s_cmp_lg_u32 s5, 56
	s_cbranch_scc1 .Lmy_gb7_topwait
	v_mov_b32_e32 v1, 1
	global_atomic_add v0, v1, s[22:23]
	s_branch .Lmy_gb7_rel

; __device__ __forceinline__ void grid_barrier(unsigned* ctr, unsigned target) {
;     ...
;         while (__hip_atomic_load(ctr, __ATOMIC_RELAXED, __HIP_MEMORY_SCOPE_AGENT) < target) { __builtin_amdgcn_s_sleep(2); if (++spins > (1u << 24)) break; }
;         __builtin_amdgcn_fence(__ATOMIC_ACQUIRE, "agent");
.Lmy_gb7_topspin:
	global_load_dword v1, v0, s[22:23] sc1
	s_waitcnt vmcnt(0)
	v_readfirstlane_b32 s5, v1
	s_nop 1
	s_cmp_ge_u32 s5, 7
	s_cbranch_scc1 .Lmy_gb7_rel
	s_sleep 1
	s_add_i32 s6, s6, -1
	s_cmp_lg_u32 s6, 0
	s_cbranch_scc1 .Lmy_gb7_topspin

;     __host__ __device__ bool next(int i, Unit& u) const {
;         const long L = (long)i * G + c; if (L >= nwg) return false;
;         int wgid = (int)L; { const int q = nwg / NXCD, r = nwg % NXCD, xcd = wgid % NXCD, off = wgid / NXCD; wgid = (xcd < r ? xcd * (q + 1) : r * (q + 1) + (xcd - r) * q) + off; }
;         const int nig = WGM * nN, gid = wgid / nig, fm = gid * WGM, gsz = (nM - fm) < WGM ? (nM - fm) : WGM;
;         u.pm = fm + ((wgid % nig) % gsz); u.pn = (wgid % nig) / gsz; return true;
; __global__ void __launch_bounds__(512, 2) mk_fwd(Args a) {
;     ...
;     { pg8::Gemm g{Hb, Wdn_t, TT, DM, DFF}; pg8::StaticOrder S; S.init(TT, DM, G, vbx); pg8::EpiFinal E{out, X1B, SSQ2, bar_ctr + 1024, g_fin};
;       pg8::gemm_phase<pg8::EpiFinal, pg8::StaticOrder, true, true>(lds, g, S, E); }
.Lmy_gb7_done:
.LBB0_415:
	s_or_b64 exec, exec, s[0:1]
	s_barrier
	s_and_b64 vcc, exec, s[2:3]
	v_readfirstlane_b32 s0, v254
	s_cbranch_vccnz .LBB0_418
	s_lshr_b32 s1, s76, 29
	s_add_i32 s1, s33, s1
	s_ashr_i32 s4, s1, 3
	s_and_b32 s1, s1, -8
	s_sub_i32 s1, s33, s1
	s_cmp_lt_i32 s1, 0
	s_movk_i32 s5, 0xa1
	s_cselect_b32 s5, s5, 0xa0
	s_mul_i32 s1, s1, s5
	s_add_i32 s1, s1, s4
	s_ashr_i32 s4, s1, 31
	s_lshr_b32 s4, s4, 27
	s_add_i32 s4, s1, s4
	s_ashr_i32 s5, s4, 5
	s_and_b32 s4, s4, 0xffe0
	s_sub_i32 s1, s1, s4
	s_bfe_i32 s4, s1, 0x80000
	s_bfe_u32 s4, s4, 0x3000c
	s_add_i32 s4, s1, s4
	s_bfe_i32 s6, s4, 0x80000
	s_and_b32 s4, s4, 0xf8
	s_sub_i32 s1, s1, s4
	s_lshl_b32 s5, s5, 3
	s_sext_i32_i16 s6, s6
	s_sext_i32_i8 s1, s1
	s_add_i32 s38, s5, s1
	s_ashr_i32 s6, s6, 3
	s_and_b64 vcc, exec, s[2:3]
	s_cbranch_vccz .LBB0_419
